# prep_pool: software prefetch of the wave's next row (one dummy dword load per 128-B line, issued after the row's own loads; counted waits +1)
# baseline (speedup 1.0000x reference)
.LBB0_291:
	s_and_b64 vcc, exec, s[2:3]
	s_cbranch_vccz .LBB0_476
	v_readlane_b32 s2, v255, 12
	s_cmp_gt_i32 s2, 2
	s_mov_b64 s[2:3], -1
	s_cbranch_scc0 .LBB0_473
	v_readlane_b32 s2, v255, 12
	s_cmp_lt_i32 s2, 4
	s_mov_b64 s[2:3], -1
	s_cbranch_scc1 .LBB0_437
	v_readlane_b32 s2, v255, 12
	s_cmp_gt_i32 s2, 4
	s_mov_b64 s[2:3], -1
	s_cbranch_scc0 .LBB0_317
	v_readlane_b32 s37, v255, 9
	s_lshr_b32 s37, s37, 7
	s_sub_i32 s37, s37, s18
	s_max_i32 s37, s37, 0
	s_lshl_b32 s89, s37, 1
	s_cmp_gt_i32 s89, s18
	s_cselect_b32 s37, 0, s37
	s_sub_i32 s36, s20, s37
	s_sub_i32 s88, s18, s37
	s_lshl_b32 s36, s36, 3
	s_lshl_b32 s88, s88, 3
	s_cmp_lt_i32 s36, 0
	s_cselect_b32 s36, 0x7fffff00, s36
	v_ashrrev_i32_e32 v64, 6, v160
	v_add_u32_e32 v116, s36, v64
	v_cmp_gt_i32_e32 vcc, s77, v116
	v_ashrrev_i32_e32 v65, 31, v64
	s_and_saveexec_b64 s[62:63], vcc
	s_cbranch_execz .LBB0_308
	s_load_dwordx2 s[2:3], s[0:1], 0x70
	s_load_dwordx2 s[6:7], s[0:1], 0x60
	v_readlane_b32 s9, v255, 8
	s_lshl_b32 s24, s9, 7
	s_ashr_i32 s25, s24, 31
	s_lshl_b64 s[24:25], s[24:25], 2
	s_waitcnt lgkmcnt(0)
	s_add_u32 s2, s2, s24
	s_mul_i32 s24, s9, 0xc0
	s_addc_u32 s3, s3, s25
	s_ashr_i32 s25, s24, 31
	s_lshl_b64 s[24:25], s[24:25], 2
	s_add_u32 s6, s6, s24
	s_waitcnt vmcnt(0)
	v_and_b32_e32 v7, 63, v160
	v_bfe_u32 v0, v160, 4, 2
	s_addc_u32 s7, s7, s25
	v_lshlrev_b32_e64 v48, v0, 2
	v_lshlrev_b32_e32 v0, 2, v7
	global_load_dword v50, v0, s[6:7]
	global_load_dword v51, v0, s[6:7] offset:256
	global_load_dword v52, v0, s[6:7] offset:512
	global_load_dword v53, v0, s[2:3]
	global_load_dword v54, v0, s[2:3] offset:256
	v_and_b32_e32 v0, 64, v197
	v_add_u32_e32 v0, 64, v0
	v_xor_b32_e32 v1, 1, v197
	v_cmp_lt_i32_e32 vcc, v1, v0
	s_ashr_i32 s37, s36, 31
	v_lshl_add_u64 v[14:15], v[64:65], 0, s[36:37]
	v_cndmask_b32_e32 v1, v197, v1, vcc
	v_lshlrev_b32_e32 v55, 2, v1
	v_xor_b32_e32 v1, 2, v197
	v_cmp_lt_i32_e32 vcc, v1, v0
	v_lshlrev_b64 v[4:5], 11, v[14:15]
	s_mov_b64 s[2:3], 0x800600
	v_cndmask_b32_e32 v1, v197, v1, vcc
	v_lshlrev_b32_e32 v56, 2, v1
	v_xor_b32_e32 v1, 4, v197
	v_cmp_lt_i32_e32 vcc, v1, v0
	s_movk_i32 s6, 0x8c0
	v_lshlrev_b32_e32 v16, 1, v7
	v_cndmask_b32_e32 v1, v197, v1, vcc
	v_lshlrev_b32_e32 v57, 2, v1
	v_xor_b32_e32 v1, 8, v197
	v_cmp_lt_i32_e32 vcc, v1, v0
	v_mov_b32_e32 v17, v157
	v_and_b32_e32 v12, 31, v160
	v_cndmask_b32_e32 v1, v197, v1, vcc
	v_lshlrev_b32_e32 v58, 2, v1
	v_xor_b32_e32 v1, 16, v197
	v_cmp_lt_i32_e32 vcc, v1, v0
	v_cmp_gt_u32_e64 s[38:39], 16, v12
	v_mov_b32_e32 v6, 0
	v_cndmask_b32_e32 v1, v197, v1, vcc
	v_lshlrev_b32_e32 v59, 2, v1
	v_xor_b32_e32 v1, 32, v197
	v_cmp_lt_i32_e32 vcc, v1, v0
	s_ashr_i32 s89, s88, 31
	v_lshrrev_b32_e32 v49, 1, v48
	v_cndmask_b32_e32 v0, v197, v1, vcc
	v_and_b32_e32 v1, 7, v160
	v_cvt_f32_ubyte0_e32 v2, v1
	v_mul_f32_e32 v2, 0xbfd49a78, v2
	v_lshlrev_b32_e32 v60, 2, v0
	v_bfe_u32 v0, v160, 3, 1
	v_exp_f32_e32 v61, v2
	v_lshrrev_b32_e32 v2, 1, v160
	v_cmp_eq_u32_e64 s[40:41], 0, v0
	v_lshlrev_b32_e32 v0, 4, v0
	v_and_b32_e32 v2, 8, v2
	v_or3_b32 v0, v0, v2, v1
	v_lshlrev_b32_e32 v156, 1, v0
	v_lshl_add_u64 v[0:1], s[46:47], 0, v[156:157]
	v_lshlrev_b32_e32 v156, 3, v7
	v_or_b32_e32 v4, v4, v156
	v_lshl_add_u64 v[4:5], v[4:5], 0, s[2:3]
	v_mad_u64_u32 v[10:11], s[2:3], v14, s6, 0
	v_mad_u64_u32 v[8:9], s[2:3], v14, s6, v[16:17]
	v_mad_i32_i24 v9, v15, s6, v9
	s_mov_b64 s[2:3], 0x4c00100
	v_mad_i32_i24 v11, v15, s6, v11
	v_lshl_add_u64 v[8:9], v[8:9], 0, s[2:3]
	v_lshl_or_b32 v10, v12, 1, v10
	s_mov_b64 s[2:3], 0x4c00280
	v_lshl_add_u64 v[10:11], v[10:11], 0, s[2:3]
	v_mad_u64_u32 v[12:13], s[2:3], v14, s6, v[156:157]
	v_mad_i32_i24 v13, v15, s6, v13
	s_mov_b64 s[2:3], 0x4c006c0
	s_movk_i32 s6, 0x300
	v_lshl_add_u64 v[12:13], v[12:13], 0, s[2:3]
	v_mad_u64_u32 v[18:19], s[2:3], v14, s6, 0
	v_mad_i32_i24 v15, v15, s6, v19
	v_or_b32_e32 v14, v18, v16
	s_mov_b64 s[2:3], 0xb860180
	v_cmp_gt_u32_e64 s[42:43], 32, v7
	v_lshl_add_u64 v[2:3], s[30:31], 0, v[156:157]
	s_lshl_b64 s[66:67], s[88:89], 11
	s_mul_hi_i32 s69, s88, 0x8c0
	s_mul_i32 s68, s88, 0x8c0
	v_lshl_add_u64 v[14:15], v[14:15], 0, s[2:3]
	s_mul_hi_i32 s81, s88, 0x300
	s_mul_i32 s80, s88, 0x300
	s_mov_b64 s[84:85], 0
	v_mov_b32_e32 v62, v116
	v_mov_b32_e32 v7, v6
	v_mov_b32_e32 v16, v6
	v_mov_b32_e32 v17, v6
	v_mov_b32_e32 v18, v6
	v_mov_b32_e32 v19, v6
	v_mov_b32_e32 v20, v6
	v_mov_b32_e32 v21, v6
	v_mov_b32_e32 v22, v6
	v_mov_b32_e32 v23, v6
	v_mov_b32_e32 v24, v6
	v_mov_b32_e32 v25, v6
	v_mov_b32_e32 v26, v6
	v_mov_b32_e32 v27, v6
	v_mov_b32_e32 v28, v6
	v_mov_b32_e32 v29, v6
	v_mov_b32_e32 v30, v6
	v_mov_b32_e32 v31, v6
	v_mov_b32_e32 v32, v6
	v_mov_b32_e32 v33, v6
	v_mov_b32_e32 v34, v6
	v_mov_b32_e32 v35, v6
	v_mov_b32_e32 v36, v6
	v_mov_b32_e32 v37, v6
	v_mov_b32_e32 v38, v6
	v_mov_b32_e32 v39, v6
	v_mov_b32_e32 v40, v6
	v_mov_b32_e32 v41, v6
	v_mov_b32_e32 v42, v6
	v_mov_b32_e32 v43, v6
	v_mov_b32_e32 v44, v6
	v_mov_b32_e32 v45, v6
	v_min_u32_e32 v206, 18, v197
	v_lshlrev_b32_e32 v206, 7, v206
	v_lshlrev_b32_e32 v207, 1, v197
	v_sub_u32_e32 v206, v206, v207
	v_add_u32_e32 v206, 0xffffff00, v206
	s_branch .LBB0_298

.LBB0_300:
	s_or_b64 exec, exec, s[6:7]
	v_add3_u32 v208, v8, s68, v206
	global_load_dword v209, v208, s[26:27]
	s_waitcnt vmcnt(5)
	v_lshlrev_b32_e32 v96, 16, v88
	s_waitcnt vmcnt(4)
	v_lshlrev_b32_e32 v89, 16, v89
	v_lshlrev_b32_e32 v88, 16, v87
	s_waitcnt vmcnt(2)
	v_lshlrev_b32_e32 v93, 16, v86
	v_lshlrev_b32_e32 v92, 16, v85
	v_pk_mul_f32 v[90:91], v[88:89], v[88:89]
	v_pk_mul_f32 v[94:95], v[92:93], v[92:93]
	v_fma_f32 v87, v96, v96, v90
	v_mov_b32_e32 v86, v94
	v_mov_b32_e32 v90, v95
	v_pk_add_f32 v[86:87], v[86:87], v[90:91]
	s_brev_b32 s2, 60
	s_mov_b32 s3, 0x3baaaaab
	s_waitcnt vmcnt(1)
	v_lshlrev_b32_e32 v84, 16, v84
	s_waitcnt lgkmcnt(0)
	s_nop 1
	v_add_f32_dpp v86, v86, v86 quad_perm:[1,0,3,2] row_mask:0xf bank_mask:0xf
	v_add_f32_dpp v87, v87, v87 quad_perm:[1,0,3,2] row_mask:0xf bank_mask:0xf
	s_waitcnt lgkmcnt(0)
	s_nop 1
	v_add_f32_dpp v86, v86, v86 quad_perm:[2,3,0,1] row_mask:0xf bank_mask:0xf
	v_add_f32_dpp v87, v87, v87 quad_perm:[2,3,0,1] row_mask:0xf bank_mask:0xf
	s_waitcnt lgkmcnt(0)
	s_nop 1
	v_add_f32_dpp v86, v86, v86 row_half_mirror row_mask:0xf bank_mask:0xf
	v_add_f32_dpp v87, v87, v87 row_half_mirror row_mask:0xf bank_mask:0xf
	s_waitcnt lgkmcnt(0)
	s_nop 1
	v_add_f32_dpp v86, v86, v86 row_mirror row_mask:0xf bank_mask:0xf
	v_add_f32_dpp v87, v87, v87 row_mirror row_mask:0xf bank_mask:0xf
	s_waitcnt lgkmcnt(0)
	v_mov_b32_e32 v90, v86
	v_mov_b32_e32 v91, v87
	s_nop 1
	v_permlane16_swap_b32_e32 v86, v90
	v_permlane16_swap_b32_e32 v87, v91
	v_pk_add_f32 v[86:87], v[86:87], v[90:91]
	s_waitcnt lgkmcnt(0)
	v_mov_b32_e32 v90, v86
	v_mov_b32_e32 v91, v87
	s_nop 1
	v_permlane32_swap_b32_e32 v86, v90
	v_permlane32_swap_b32_e32 v87, v91
	v_pk_add_f32 v[86:87], v[86:87], v[90:91]
	s_nop 0
	v_pk_fma_f32 v[86:87], v[86:87], s[2:3], v[158:159] op_sel_hi:[1,1,0]
	s_nop 0
	v_mul_f32_e32 v85, 0x4b800000, v87
	v_cmp_gt_f32_e64 s[48:49], s82, v87
	v_cmp_gt_f32_e64 s[46:47], s82, v86
	s_nop 0
	v_cndmask_b32_e64 v85, v87, v85, s[48:49]
	v_rsq_f32_e32 v85, v85
	s_nop 0
	v_mul_f32_e32 v87, 0x45800000, v85
	v_cndmask_b32_e64 v85, v85, v87, s[48:49]
	v_mul_f32_e32 v87, 0x4b800000, v86
	v_cndmask_b32_e64 v86, v86, v87, s[46:47]
	v_rsq_f32_e32 v86, v86
	s_nop 0
	v_mul_f32_e32 v87, 0x45800000, v86
	v_cndmask_b32_e64 v90, v86, v87, s[46:47]
	v_mul_f32_e32 v86, v85, v88
	v_mul_f32_e32 v86, v50, v86
	v_cvt_pk_bf16_f32 v88, v86, v157
	v_lshl_add_u64 v[86:87], s[26:27], 0, v[14:15]
	global_store_short v[86:87], v88, off offset:-384
	v_mul_f32_e32 v88, v85, v96
	v_mul_f32_e32 v85, v85, v89
	v_mul_f32_e32 v88, v51, v88
	v_mul_f32_e32 v85, v52, v85
	v_cvt_pk_bf16_f32 v88, v88, v157
	global_store_short v[86:87], v88, off offset:-256
	v_cvt_pk_bf16_f32 v85, v85, v157
	global_store_short v[86:87], v85, off offset:-128
	v_mul_f32_e32 v85, v90, v92
	v_mul_f32_e32 v85, v53, v85
	v_cvt_pk_bf16_f32 v85, v85, v157
	global_store_short v[86:87], v85, off
	v_mul_f32_e32 v85, v90, v93
	v_mul_f32_e32 v85, v54, v85
	v_cvt_pk_bf16_f32 v85, v85, v157
	global_store_short v[86:87], v85, off offset:128
	global_store_short v[86:87], v157, off offset:256
	ds_bpermute_b32 v85, v58, v84
	s_and_saveexec_b64 s[2:3], s[44:45]
	s_xor_b64 s[2:3], exec, s[2:3]
	s_cbranch_execnz .LBB0_304
	s_andn2_saveexec_b64 s[2:3], s[2:3]
	s_cbranch_execnz .LBB0_305
